# early-drain: 16th-from-last arriver of each XCD issues an extra buffer_wbl2 at every grid barrier
# baseline (speedup 1.0000x reference)
.LBB0_60:
	s_or_b64 exec, exec, s[10:11]
	s_cmp_eq_u32 s3, 0
	s_cselect_b64 vcc, -1, 0
	s_cmp_eq_u32 s3, 1
	v_cndmask_b32_e32 v18, 0, v15, vcc
	s_cselect_b64 vcc, -1, 0
	s_cmp_eq_u32 s3, 2
	v_cndmask_b32_e32 v18, v18, v3, vcc
	s_cselect_b64 vcc, -1, 0
	s_cmp_eq_u32 s3, 3
	v_cndmask_b32_e32 v18, v18, v4, vcc
	s_cselect_b64 vcc, -1, 0
	s_cmp_eq_u32 s3, 4
	v_cndmask_b32_e32 v18, v18, v5, vcc
	s_cselect_b64 vcc, -1, 0
	s_cmp_eq_u32 s3, 5
	v_cndmask_b32_e32 v18, v18, v6, vcc
	s_cselect_b64 vcc, -1, 0
	s_cmp_eq_u32 s3, 6
	v_cndmask_b32_e32 v18, v18, v7, vcc
	s_cselect_b64 vcc, -1, 0
	s_cmp_eq_u32 s3, 7
	v_cndmask_b32_e32 v18, v18, v8, vcc
	s_cselect_b64 vcc, -1, 0
	s_cmp_eq_u32 s3, 8
	v_cndmask_b32_e32 v18, v18, v9, vcc
	s_cselect_b64 vcc, -1, 0
	s_cmp_eq_u32 s3, 9
	v_cndmask_b32_e32 v18, v18, v10, vcc
	s_cselect_b64 vcc, -1, 0
	s_cmp_eq_u32 s3, 10
	v_cndmask_b32_e32 v18, v18, v11, vcc
	s_cselect_b64 vcc, -1, 0
	s_cmp_eq_u32 s3, 11
	v_cndmask_b32_e32 v18, v18, v12, vcc
	s_cselect_b64 vcc, -1, 0
	s_cmp_eq_u32 s3, 12
	v_cndmask_b32_e32 v18, v18, v13, vcc
	s_cselect_b64 vcc, -1, 0
	s_cmp_eq_u32 s3, 13
	v_cndmask_b32_e32 v18, v18, v14, vcc
	s_cselect_b64 vcc, -1, 0
	s_cmp_eq_u32 s3, 14
	v_cndmask_b32_e32 v18, v18, v1, vcc
	s_cselect_b64 vcc, -1, 0
	s_cmp_eq_u32 s3, 15
	v_cndmask_b32_e32 v18, v18, v2, vcc
	s_cselect_b64 vcc, -1, 0
	v_cndmask_b32_e32 v18, v18, v0, vcc
	v_cmp_ne_u32_e32 vcc, 0, v15
	v_max_u32_e32 v180, 1, v18
	s_waitcnt vmcnt(0)
	v_readfirstlane_b32 s8, v17
	v_cndmask_b32_e64 v15, 0, 1, vcc
	v_cmp_ne_u32_e32 vcc, 0, v3
	s_nop 1
	v_addc_co_u32_e32 v3, vcc, 0, v15, vcc
	v_cmp_ne_u32_e32 vcc, 0, v4
	s_nop 1
	v_cndmask_b32_e64 v4, 0, 1, vcc
	v_cmp_ne_u32_e32 vcc, 0, v5
	v_cvt_f32_u32_e32 v5, v180
	s_nop 0
	v_addc_co_u32_e32 v3, vcc, v3, v4, vcc
	v_cmp_ne_u32_e32 vcc, 0, v6
	s_nop 1
	v_cndmask_b32_e64 v4, 0, 1, vcc
	v_cmp_ne_u32_e32 vcc, 0, v7
	s_nop 1
	v_addc_co_u32_e32 v3, vcc, v3, v4, vcc
	v_cmp_ne_u32_e32 vcc, 0, v8
	s_nop 1
	v_cndmask_b32_e64 v4, 0, 1, vcc
	v_cmp_ne_u32_e32 vcc, 0, v9
	s_nop 1
	v_addc_co_u32_e32 v3, vcc, v3, v4, vcc
	v_cmp_ne_u32_e32 vcc, 0, v10
	s_nop 1
	v_cndmask_b32_e64 v4, 0, 1, vcc
	v_cmp_ne_u32_e32 vcc, 0, v11
	s_nop 1
	v_addc_co_u32_e32 v3, vcc, v3, v4, vcc
	v_cmp_ne_u32_e32 vcc, 0, v12
	s_nop 1
	v_cndmask_b32_e64 v4, 0, 1, vcc
	v_cmp_ne_u32_e32 vcc, 0, v13
	s_nop 1
	v_addc_co_u32_e32 v3, vcc, v3, v4, vcc
	v_cmp_ne_u32_e32 vcc, 0, v14
	s_nop 1
	v_cndmask_b32_e64 v4, 0, 1, vcc
	v_cmp_ne_u32_e32 vcc, 0, v1
	s_nop 1
	v_addc_co_u32_e32 v1, vcc, v3, v4, vcc
	v_rcp_iflag_f32_e32 v3, v5
	v_cmp_ne_u32_e32 vcc, 0, v2
	s_nop 1
	v_cndmask_b32_e64 v2, 0, 1, vcc
	v_cmp_ne_u32_e32 vcc, 0, v0
	s_nop 1
	v_addc_co_u32_e32 v0, vcc, v1, v2, vcc
	v_mul_f32_e32 v1, 0x4f7ffffe, v3
	v_cvt_u32_f32_e32 v1, v1
	v_sub_u32_e32 v3, 0, v180
	v_add_u32_e32 v2, s8, v16
	v_mul_lo_u32 v3, v3, v1
	v_mul_hi_u32 v3, v1, v3
	v_add_u32_e32 v1, v1, v3
	v_mul_hi_u32 v1, v2, v1
	v_mul_lo_u32 v3, v1, v180
	v_sub_u32_e32 v3, v2, v3
	v_add_u32_e32 v4, 1, v1
	v_cmp_ge_u32_e32 vcc, v3, v180
	v_add_u32_e32 v2, 1, v2
	s_nop 0
	v_cndmask_b32_e32 v1, v1, v4, vcc
	v_sub_u32_e32 v4, v3, v180
	v_cndmask_b32_e32 v3, v3, v4, vcc
	v_add_u32_e32 v4, 1, v1
	v_cmp_ge_u32_e32 vcc, v3, v180
	s_nop 1
	v_cndmask_b32_e32 v1, v1, v4, vcc
	v_mul_lo_u32 v3, v180, v1
	v_add_u32_e32 v3, v3, v180
	v_add_u32_e32 v4, 16, v2
	v_cmp_eq_u32_e32 vcc, v4, v3
	s_and_saveexec_b64 s[8:9], vcc
	s_cbranch_execz .Ledr_1
	buffer_wbl2 sc1
.Ledr_1:
	s_or_b64 exec, exec, s[8:9]
	v_cmp_ne_u32_e32 vcc, v2, v3
	s_and_saveexec_b64 s[8:9], vcc
	s_xor_b64 s[8:9], exec, s[8:9]
	s_cbranch_execz .LBB0_74
	v_mov_b32_e32 v2, 0x2000
	global_load_dword v2, v2, s[6:7] offset:1024 sc1
	s_add_u32 s12, s6, 0x2400
	s_addc_u32 s13, s7, 0
	s_waitcnt vmcnt(0)
	v_cmp_eq_u32_e32 vcc, v2, v1
	s_and_saveexec_b64 s[10:11], vcc
	s_cbranch_execz .LBB0_73
	s_mov_b32 s33, 1
	s_mov_b64 s[14:15], 0
	v_mov_b32_e32 v2, 0
	s_branch .LBB0_64

.LBB0_429:
	s_or_b64 exec, exec, s[8:9]
	v_cvt_f32_u32_e32 v2, v180
	s_waitcnt vmcnt(0)
	v_readfirstlane_b32 s6, v1
	v_rcp_iflag_f32_e32 v2, v2
	s_nop 0
	v_add_u32_e32 v0, s6, v0
	v_add_u32_e32 v4, 1, v0
	v_mul_f32_e32 v1, 0x4f7ffffe, v2
	v_cvt_u32_f32_e32 v1, v1
	v_sub_u32_e32 v2, 0, v180
	v_mul_lo_u32 v2, v2, v1
	v_mul_hi_u32 v2, v1, v2
	v_add_u32_e32 v1, v1, v2
	v_mul_hi_u32 v1, v0, v1
	v_mul_lo_u32 v2, v1, v180
	v_sub_u32_e32 v0, v0, v2
	v_add_u32_e32 v3, 1, v1
	v_cmp_ge_u32_e32 vcc, v0, v180
	v_sub_u32_e32 v2, v0, v180
	s_nop 0
	v_cndmask_b32_e32 v1, v1, v3, vcc
	v_cndmask_b32_e32 v0, v0, v2, vcc
	v_add_u32_e32 v2, 1, v1
	v_cmp_ge_u32_e32 vcc, v0, v180
	s_nop 1
	v_cndmask_b32_e32 v0, v1, v2, vcc
	v_mad_u64_u32 v[2:3], s[6:7], v180, v0, v[180:181]
	v_add_u32_e32 v3, 16, v4
	v_cmp_eq_u32_e32 vcc, v3, v2
	s_and_saveexec_b64 s[6:7], vcc
	s_cbranch_execz .Ledr_2
	buffer_wbl2 sc1
.Ledr_2:
	s_or_b64 exec, exec, s[6:7]
	v_cmp_ne_u32_e32 vcc, v4, v2
	s_and_saveexec_b64 s[6:7], vcc
	s_xor_b64 s[6:7], exec, s[6:7]
	s_cbranch_execz .LBB0_443
	v_mov_b32_e32 v1, 0x2000
	global_load_dword v1, v1, s[4:5] offset:1024 sc1
	s_add_u32 s12, s4, 0x2400
	s_addc_u32 s13, s5, 0
	s_waitcnt vmcnt(0)
	v_cmp_eq_u32_e32 vcc, v1, v0
	s_and_saveexec_b64 s[8:9], vcc
	s_cbranch_execz .LBB0_442
	s_add_u32 s10, s20, 0x1d750200
	s_addc_u32 s11, s21, 0
	s_mov_b32 s29, 1
	s_mov_b64 s[14:15], 0
	v_mov_b32_e32 v1, 0
	s_branch .LBB0_433

.LBB0_1186:
	s_or_b64 exec, exec, s[10:11]
	v_cvt_f32_u32_e32 v2, v180
	s_waitcnt vmcnt(0)
	v_readfirstlane_b32 s3, v1
	v_rcp_iflag_f32_e32 v2, v2
	s_nop 0
	v_add_u32_e32 v0, s3, v0
	v_add_u32_e32 v4, 1, v0
	v_mul_f32_e32 v1, 0x4f7ffffe, v2
	v_cvt_u32_f32_e32 v1, v1
	v_sub_u32_e32 v2, 0, v180
	v_mul_lo_u32 v2, v2, v1
	v_mul_hi_u32 v2, v1, v2
	v_add_u32_e32 v1, v1, v2
	v_mul_hi_u32 v1, v0, v1
	v_mul_lo_u32 v2, v1, v180
	v_sub_u32_e32 v0, v0, v2
	v_add_u32_e32 v3, 1, v1
	v_cmp_ge_u32_e32 vcc, v0, v180
	v_sub_u32_e32 v2, v0, v180
	s_nop 0
	v_cndmask_b32_e32 v1, v1, v3, vcc
	v_cndmask_b32_e32 v0, v0, v2, vcc
	v_add_u32_e32 v2, 1, v1
	v_cmp_ge_u32_e32 vcc, v0, v180
	s_nop 1
	v_cndmask_b32_e32 v0, v1, v2, vcc
	v_mad_u64_u32 v[2:3], s[8:9], v180, v0, v[180:181]
	v_add_u32_e32 v3, 16, v4
	v_cmp_eq_u32_e32 vcc, v3, v2
	s_and_saveexec_b64 s[8:9], vcc
	s_cbranch_execz .Ledr_7
	buffer_wbl2 sc1
.Ledr_7:
	s_or_b64 exec, exec, s[8:9]
	v_cmp_ne_u32_e32 vcc, v4, v2
	s_and_saveexec_b64 s[8:9], vcc
	s_xor_b64 s[8:9], exec, s[8:9]
	s_cbranch_execz .LBB0_1200
	v_mov_b32_e32 v1, 0x2000
	global_load_dword v1, v1, s[4:5] offset:1024 sc1
	s_add_u32 s14, s4, 0x2400
	s_addc_u32 s15, s5, 0
	s_waitcnt vmcnt(0)
	v_cmp_eq_u32_e32 vcc, v1, v0
	s_and_saveexec_b64 s[10:11], vcc
	s_cbranch_execz .LBB0_1199
	s_add_u32 s12, s20, 0x1d750200
	s_addc_u32 s13, s21, 0
	s_mov_b32 s3, 1
	s_mov_b64 s[16:17], 0
	v_mov_b32_e32 v1, 0
	s_branch .LBB0_1190
